# v61 + nt on the P0 weight-transpose stores
# speedup vs baseline: 1.0024x; 1.0024x over previous
.LBB0_22:
	s_or_b64 exec, exec, s[4:5]
	v_add_u32_e32 v4, 0x14a0, v10
	s_waitcnt vmcnt(0)
	ds_write2_b32 v4, v0, v1 offset1:1
	v_add_u32_e32 v0, 0x14a8, v10
	ds_write2_b32 v0, v2, v3 offset1:1
	s_waitcnt lgkmcnt(0)
	ds_read2_b32 v[4:5], v52 offset0:33 offset1:41
	ds_read2_b32 v[6:7], v52 offset1:8
	ds_read2_b32 v[8:9], v52 offset0:66 offset1:74
	ds_read2_b32 v[10:11], v52 offset0:99 offset1:107
	ds_read2_b32 v[38:39], v52 offset0:132 offset1:140
	ds_read2_b32 v[66:67], v52 offset0:165 offset1:173
	ds_read2_b32 v[68:69], v52 offset0:198 offset1:206
	ds_read2_b32 v[70:71], v52 offset0:231 offset1:239
	v_add_u32_e32 v74, s28, v12
	s_ashr_i32 s31, s30, 31
	v_ashrrev_i32_e32 v75, 31, v74
	v_lshl_add_u64 v[72:73], s[30:31], 1, v[36:37]
	v_lshlrev_b64 v[76:77], 11, v[74:75]
	s_waitcnt lgkmcnt(6)
	v_cvt_pk_bf16_f32 v0, v6, v4
	s_waitcnt lgkmcnt(4)
	v_cvt_pk_bf16_f32 v1, v8, v10
	s_waitcnt lgkmcnt(2)
	v_cvt_pk_bf16_f32 v2, v38, v66
	s_waitcnt lgkmcnt(0)
	v_cvt_pk_bf16_f32 v3, v68, v70
	v_lshl_add_u64 v[76:77], v[72:73], 0, v[76:77]
	v_add_u32_e32 v4, 8, v74
	global_store_dwordx4 v[76:77], v[0:3], off nt
	s_mov_b32 s30, s82
	s_nop 0
	v_cvt_pk_bf16_f32 v0, v7, v5
	v_ashrrev_i32_e32 v5, 31, v4
	v_cvt_pk_bf16_f32 v1, v9, v11
	v_cvt_pk_bf16_f32 v2, v39, v67
	v_cvt_pk_bf16_f32 v3, v69, v71
	v_lshlrev_b64 v[4:5], 11, v[4:5]
	ds_read2_b32 v[6:7], v52 offset0:49 offset1:57
	ds_read2_b32 v[8:9], v52 offset0:16 offset1:24
	ds_read2_b32 v[10:11], v52 offset0:82 offset1:90
	ds_read2_b32 v[38:39], v52 offset0:115 offset1:123
	ds_read2_b32 v[66:67], v52 offset0:148 offset1:156
	ds_read2_b32 v[68:69], v52 offset0:181 offset1:189
	ds_read2_b32 v[70:71], v52 offset0:214 offset1:222
	ds_read2_b32 v[76:77], v52 offset0:247 offset1:255
	v_lshl_add_u64 v[4:5], v[72:73], 0, v[4:5]
	global_store_dwordx4 v[4:5], v[0:3], off nt
	v_add_u32_e32 v4, 16, v74
	v_ashrrev_i32_e32 v5, 31, v4
	v_lshlrev_b64 v[4:5], 11, v[4:5]
	s_waitcnt lgkmcnt(6)
	v_cvt_pk_bf16_f32 v0, v8, v6
	s_waitcnt lgkmcnt(4)
	v_cvt_pk_bf16_f32 v1, v10, v38
	s_waitcnt lgkmcnt(2)
	v_cvt_pk_bf16_f32 v2, v66, v68
	s_waitcnt lgkmcnt(0)
	v_cvt_pk_bf16_f32 v3, v70, v76
	v_lshl_add_u64 v[4:5], v[72:73], 0, v[4:5]
	global_store_dwordx4 v[4:5], v[0:3], off nt
	v_add_u32_e32 v4, 24, v74
	v_ashrrev_i32_e32 v5, 31, v4
	v_lshlrev_b64 v[4:5], 11, v[4:5]
	v_cvt_pk_bf16_f32 v0, v9, v7
	v_cvt_pk_bf16_f32 v1, v11, v39
	v_cvt_pk_bf16_f32 v2, v67, v69
	v_cvt_pk_bf16_f32 v3, v71, v77
	v_lshl_add_u64 v[4:5], v[72:73], 0, v[4:5]
	global_store_dwordx4 v[4:5], v[0:3], off nt
	s_waitcnt lgkmcnt(0)

.LBB0_24:
	s_cmpk_gt_i32 s47, 0x67f
	s_mov_b64 s[0:1], -1
	s_cbranch_scc0 .LBB0_95
	s_cmpk_gt_u32 s47, 0x87f
	s_cbranch_scc0 .LBB0_92
	s_cmpk_gt_u32 s47, 0xa7f
	s_cbranch_scc0 .LBB0_89
	s_cmpk_gt_u32 s47, 0xd7f
	s_cbranch_scc0 .LBB0_69
	s_cmpk_gt_u32 s47, 0xf7f
	s_cbranch_scc0 .LBB0_66
	s_cmpk_gt_u32 s47, 0x107f
	s_cbranch_scc0 .LBB0_63
	s_cmpk_gt_u32 s47, 0x117f
	s_cbranch_scc0 .LBB0_60
	s_cmpk_gt_u32 s47, 0x1c7f
	s_cbranch_scc0 .LBB0_41
	s_cmpk_gt_u32 s47, 0x277f
	s_cbranch_scc0 .LBB0_38
	s_and_b32 s4, s38, 0x3e0
	v_or_b32_e32 v0, s4, v41
	v_or_b32_e32 v1, s4, v43
	v_or_b32_e32 v4, s4, v45
	v_or_b32_e32 v5, s4, v47
	s_cmpk_gt_u32 s47, 0x2cff
	v_lshlrev_b32_e32 v14, 2, v0
	v_or_b32_e32 v3, s4, v12
	v_mul_u32_u24_e32 v2, 0xb00, v1
	v_mul_u32_u24_e32 v1, 0xb00, v4
	v_mul_u32_u24_e32 v0, 0xb00, v5
	s_cbranch_scc0 .LBB0_35
	s_and_b32 s0, s40, 0x1ffc0
	v_or_b32_e32 v65, s0, v45
	v_lshlrev_b32_e32 v66, 12, v65
	v_or_b32_e32 v65, s0, v47
	v_lshlrev_b32_e32 v68, 12, v65
	v_or_b32_e32 v65, s0, v48
	v_or_b32_e32 v4, s0, v12
	v_or_b32_e32 v6, s0, v43
	v_lshlrev_b32_e32 v74, 12, v65
	v_or_b32_e32 v65, s0, v49
	v_lshl_add_u64 v[38:39], s[6:7], 0, v[14:15]
	v_lshlrev_b32_e32 v4, 12, v4
	v_mov_b32_e32 v5, v15
	v_lshlrev_b32_e32 v6, 12, v6
	v_mov_b32_e32 v7, v15
	v_mov_b32_e32 v67, v15
	v_mov_b32_e32 v69, v15
	v_mov_b32_e32 v75, v15
	v_lshlrev_b32_e32 v76, 12, v65
	v_mov_b32_e32 v77, v15
	v_lshl_add_u64 v[4:5], v[38:39], 0, v[4:5]
	v_lshl_add_u64 v[8:9], v[38:39], 0, v[6:7]
	v_lshl_add_u64 v[66:67], v[38:39], 0, v[66:67]
	v_lshl_add_u64 v[70:71], v[38:39], 0, v[68:69]
	v_lshl_add_u64 v[74:75], v[38:39], 0, v[74:75]
	v_lshl_add_u64 v[78:79], v[38:39], 0, v[76:77]
	global_load_dwordx4 v[4:7], v[4:5], off
	s_nop 0
	global_load_dwordx4 v[8:11], v[8:9], off
	s_nop 0
	global_load_dwordx4 v[66:69], v[66:67], off
	s_nop 0
	global_load_dwordx4 v[70:73], v[70:71], off
	s_nop 0
	global_load_dwordx4 v[74:77], v[74:75], off
	s_nop 0
	global_load_dwordx4 v[78:81], v[78:79], off
	v_or_b32_e32 v65, s0, v50
	v_lshlrev_b32_e32 v82, 12, v65
	v_mov_b32_e32 v83, v15
	v_lshl_add_u64 v[82:83], v[38:39], 0, v[82:83]
	v_or_b32_e32 v65, s0, v51
	global_load_dwordx4 v[82:85], v[82:83], off
	v_lshlrev_b32_e32 v86, 12, v65
	v_mov_b32_e32 v87, v15
	v_lshl_add_u64 v[38:39], v[38:39], 0, v[86:87]
	global_load_dwordx4 v[86:89], v[38:39], off
	v_add_u32_e32 v65, 0x18c0, v53
	v_add_u32_e32 v94, 0x18c8, v53
	v_add_u32_e32 v95, 0x1ce0, v53
	v_add_u32_e32 v96, 0x1ce8, v53
	v_mul_u32_u24_e32 v38, 0xb00, v3
	s_lshl_b32 s28, s0, 1
	v_mov_b32_e32 v39, v15
	v_lshlrev_b32_e32 v38, 1, v38
	v_lshl_add_u64 v[92:93], v[16:17], 0, s[28:29]
	v_lshl_add_u64 v[38:39], v[92:93], 0, v[38:39]
	v_lshlrev_b32_e32 v90, 1, v2
	v_mov_b32_e32 v91, v15
	v_lshl_add_u64 v[90:91], v[92:93], 0, v[90:91]
	s_mov_b64 s[0:1], 0
	s_waitcnt vmcnt(7)
	ds_write2_b32 v53, v4, v5 offset1:1
	ds_write2_b32 v53, v6, v7 offset0:2 offset1:3
	s_waitcnt vmcnt(6)
	ds_write2_b32 v54, v8, v9 offset1:1
	ds_write2_b32 v55, v10, v11 offset1:1
	s_waitcnt vmcnt(5)
	ds_write2_b32 v56, v66, v67 offset1:1
	ds_write2_b32 v57, v68, v69 offset1:1
	s_waitcnt vmcnt(4)
	ds_write2_b32 v58, v70, v71 offset1:1
	ds_write2_b32 v59, v72, v73 offset1:1
	s_waitcnt vmcnt(3)
	ds_write2_b32 v60, v74, v75 offset1:1
	ds_write2_b32 v61, v76, v77 offset1:1
	s_waitcnt vmcnt(2)
	ds_write2_b32 v62, v78, v79 offset1:1
	ds_write2_b32 v63, v80, v81 offset1:1
	s_waitcnt vmcnt(1)
	ds_write2_b32 v65, v82, v83 offset1:1
	ds_write2_b32 v94, v84, v85 offset1:1
	s_waitcnt vmcnt(0)
	ds_write2_b32 v95, v86, v87 offset1:1
	ds_write2_b32 v96, v88, v89 offset1:1
	s_waitcnt lgkmcnt(0)
	ds_read2_b32 v[8:9], v52 offset0:33 offset1:41
	ds_read2_b32 v[10:11], v52 offset1:8
	ds_read2_b32 v[66:67], v52 offset0:66 offset1:74
	ds_read2_b32 v[68:69], v52 offset0:99 offset1:107
	ds_read2_b32 v[70:71], v52 offset0:132 offset1:140
	ds_read2_b32 v[72:73], v52 offset0:165 offset1:173
	ds_read2_b32 v[74:75], v52 offset0:198 offset1:206
	ds_read2_b32 v[76:77], v52 offset0:231 offset1:239
	ds_read2_b32 v[78:79], v52 offset0:16 offset1:24
	ds_read2_b32 v[80:81], v52 offset0:49 offset1:57
	ds_read2_b32 v[82:83], v52 offset0:82 offset1:90
	ds_read2_b32 v[84:85], v52 offset0:115 offset1:123
	s_waitcnt lgkmcnt(10)
	v_cvt_pk_bf16_f32 v4, v10, v8
	s_waitcnt lgkmcnt(8)
	v_cvt_pk_bf16_f32 v5, v66, v68
	s_waitcnt lgkmcnt(6)
	v_cvt_pk_bf16_f32 v6, v70, v72
	s_waitcnt lgkmcnt(4)
	v_cvt_pk_bf16_f32 v7, v74, v76
	global_store_dwordx4 v[38:39], v[4:7], off nt
	v_cvt_pk_bf16_f32 v8, v11, v9
	v_cvt_pk_bf16_f32 v9, v67, v69
	v_cvt_pk_bf16_f32 v10, v71, v73
	ds_read2_b32 v[38:39], v52 offset0:148 offset1:156
	ds_read2_b32 v[66:67], v52 offset0:181 offset1:189
	ds_read2_b32 v[68:69], v52 offset0:214 offset1:222
	ds_read2_b32 v[70:71], v52 offset0:247 offset1:255
	v_cvt_pk_bf16_f32 v11, v75, v77
	global_store_dwordx4 v[90:91], v[8:11], off nt
	s_waitcnt lgkmcnt(6)
	v_cvt_pk_bf16_f32 v4, v78, v80
	s_waitcnt lgkmcnt(4)
	v_cvt_pk_bf16_f32 v5, v82, v84
	v_lshlrev_b32_e32 v8, 1, v1
	v_mov_b32_e32 v9, v15
	s_waitcnt lgkmcnt(2)
	v_cvt_pk_bf16_f32 v6, v38, v66
	s_waitcnt lgkmcnt(0)
	v_cvt_pk_bf16_f32 v7, v68, v70
	v_lshl_add_u64 v[8:9], v[92:93], 0, v[8:9]
	global_store_dwordx4 v[8:9], v[4:7], off nt
	v_lshlrev_b32_e32 v8, 1, v0
	v_mov_b32_e32 v9, v15
	v_cvt_pk_bf16_f32 v4, v79, v81
	v_cvt_pk_bf16_f32 v5, v83, v85
	v_cvt_pk_bf16_f32 v6, v39, v67
	v_cvt_pk_bf16_f32 v7, v69, v71
	v_lshl_add_u64 v[8:9], v[92:93], 0, v[8:9]
	global_store_dwordx4 v[8:9], v[4:7], off nt
	s_waitcnt lgkmcnt(0)
.LBB0_35:
	s_andn2_b64 vcc, exec, s[0:1]
	s_cbranch_vccnz .LBB0_37
	s_add_i32 s0, s40, 0xb00
	s_and_b32 s0, s0, 0x1ffc0
	s_mov_b64 s[4:5], s[50:51]
	v_readlane_b32 s48, v250, 5
	v_readlane_b32 s54, v250, 11
	v_readlane_b32 s55, v250, 12
	v_or_b32_e32 v4, s0, v12
	v_or_b32_e32 v6, s0, v43
	v_lshl_add_u64 v[38:39], s[54:55], 0, v[14:15]
	v_lshlrev_b32_e32 v14, 12, v4
	v_lshl_add_u64 v[4:5], v[38:39], 0, v[14:15]
	v_lshlrev_b32_e32 v14, 12, v6
	v_lshl_add_u64 v[8:9], v[38:39], 0, v[14:15]
	v_or_b32_e32 v14, s0, v45
	v_lshlrev_b32_e32 v14, 12, v14
	v_lshl_add_u64 v[66:67], v[38:39], 0, v[14:15]
	v_or_b32_e32 v14, s0, v47
	v_lshlrev_b32_e32 v14, 12, v14
	v_lshl_add_u64 v[70:71], v[38:39], 0, v[14:15]
	v_or_b32_e32 v14, s0, v48
	v_lshlrev_b32_e32 v14, 12, v14
	v_lshl_add_u64 v[74:75], v[38:39], 0, v[14:15]
	v_or_b32_e32 v14, s0, v49
	v_lshlrev_b32_e32 v14, 12, v14
	v_lshl_add_u64 v[78:79], v[38:39], 0, v[14:15]
	global_load_dwordx4 v[4:7], v[4:5], off
	s_nop 0
	global_load_dwordx4 v[8:11], v[8:9], off
	s_nop 0
	global_load_dwordx4 v[66:69], v[66:67], off
	s_nop 0
	global_load_dwordx4 v[70:73], v[70:71], off
	s_nop 0
	global_load_dwordx4 v[74:77], v[74:75], off
	s_nop 0
	global_load_dwordx4 v[78:81], v[78:79], off
	v_or_b32_e32 v14, s0, v50
	v_lshlrev_b32_e32 v14, 12, v14
	v_lshl_add_u64 v[82:83], v[38:39], 0, v[14:15]
	v_or_b32_e32 v14, s0, v51
	global_load_dwordx4 v[82:85], v[82:83], off
	v_lshlrev_b32_e32 v14, 12, v14
	v_lshl_add_u64 v[38:39], v[38:39], 0, v[14:15]
	global_load_dwordx4 v[86:89], v[38:39], off
	v_add_u32_e32 v65, 0x18c0, v53
	v_add_u32_e32 v96, 0x18c8, v53
	v_add_u32_e32 v97, 0x1ce0, v53
	v_add_u32_e32 v98, 0x1ce8, v53
	v_mul_u32_u24_e32 v3, 0xb00, v3
	s_lshl_b32 s28, s0, 1
	v_lshl_add_u64 v[38:39], v[18:19], 0, s[28:29]
	v_lshlrev_b32_e32 v14, 1, v3
	v_lshl_add_u64 v[90:91], v[38:39], 0, v[14:15]
	v_lshlrev_b32_e32 v14, 1, v2
	v_lshl_add_u64 v[92:93], v[38:39], 0, v[14:15]
	v_lshlrev_b32_e32 v14, 1, v1
	v_lshl_add_u64 v[94:95], v[38:39], 0, v[14:15]
	v_lshlrev_b32_e32 v14, 1, v0
	v_readlane_b32 s50, v250, 7
	v_readlane_b32 s51, v250, 8
	s_mov_b64 s[50:51], s[4:5]
	v_readlane_b32 s49, v250, 6
	v_readlane_b32 s52, v250, 9
	v_readlane_b32 s53, v250, 10
	s_waitcnt vmcnt(7)
	ds_write2_b32 v53, v4, v5 offset1:1
	ds_write2_b32 v53, v6, v7 offset0:2 offset1:3
	s_waitcnt vmcnt(6)
	ds_write2_b32 v54, v8, v9 offset1:1
	ds_write2_b32 v55, v10, v11 offset1:1
	s_waitcnt vmcnt(5)
	ds_write2_b32 v56, v66, v67 offset1:1
	ds_write2_b32 v57, v68, v69 offset1:1
	s_waitcnt vmcnt(4)
	ds_write2_b32 v58, v70, v71 offset1:1
	ds_write2_b32 v59, v72, v73 offset1:1
	s_waitcnt vmcnt(3)
	ds_write2_b32 v60, v74, v75 offset1:1
	ds_write2_b32 v61, v76, v77 offset1:1
	s_waitcnt vmcnt(2)
	ds_write2_b32 v62, v78, v79 offset1:1
	ds_write2_b32 v63, v80, v81 offset1:1
	s_waitcnt vmcnt(1)
	ds_write2_b32 v65, v82, v83 offset1:1
	ds_write2_b32 v96, v84, v85 offset1:1
	s_waitcnt vmcnt(0)
	ds_write2_b32 v97, v86, v87 offset1:1
	ds_write2_b32 v98, v88, v89 offset1:1
	s_waitcnt lgkmcnt(0)
	ds_read2_b32 v[4:5], v52 offset0:33 offset1:41
	ds_read2_b32 v[6:7], v52 offset1:8
	ds_read2_b32 v[8:9], v52 offset0:66 offset1:74
	ds_read2_b32 v[10:11], v52 offset0:99 offset1:107
	ds_read2_b32 v[66:67], v52 offset0:132 offset1:140
	ds_read2_b32 v[68:69], v52 offset0:165 offset1:173
	ds_read2_b32 v[70:71], v52 offset0:198 offset1:206
	ds_read2_b32 v[72:73], v52 offset0:231 offset1:239
	ds_read2_b32 v[74:75], v52 offset0:16 offset1:24
	ds_read2_b32 v[76:77], v52 offset0:49 offset1:57
	ds_read2_b32 v[78:79], v52 offset0:82 offset1:90
	ds_read2_b32 v[80:81], v52 offset0:115 offset1:123
	ds_read2_b32 v[82:83], v52 offset0:148 offset1:156
	ds_read2_b32 v[84:85], v52 offset0:181 offset1:189
	ds_read2_b32 v[86:87], v52 offset0:214 offset1:222
	ds_read2_b32 v[88:89], v52 offset0:247 offset1:255
	s_waitcnt lgkmcnt(14)
	v_cvt_pk_bf16_f32 v0, v6, v4
	s_waitcnt lgkmcnt(12)
	v_cvt_pk_bf16_f32 v1, v8, v10
	s_waitcnt lgkmcnt(10)
	v_cvt_pk_bf16_f32 v2, v66, v68
	s_waitcnt lgkmcnt(8)
	v_cvt_pk_bf16_f32 v3, v70, v72
	v_cvt_pk_bf16_f32 v4, v7, v5
	v_cvt_pk_bf16_f32 v5, v9, v11
	v_cvt_pk_bf16_f32 v6, v67, v69
	v_cvt_pk_bf16_f32 v7, v71, v73
	s_waitcnt lgkmcnt(6)
	v_cvt_pk_bf16_f32 v8, v74, v76
	s_waitcnt lgkmcnt(4)
	v_cvt_pk_bf16_f32 v9, v78, v80
	s_waitcnt lgkmcnt(2)
	v_cvt_pk_bf16_f32 v10, v82, v84
	s_waitcnt lgkmcnt(0)
	v_cvt_pk_bf16_f32 v11, v86, v88
	v_cvt_pk_bf16_f32 v66, v75, v77
	v_cvt_pk_bf16_f32 v67, v79, v81
	v_cvt_pk_bf16_f32 v68, v83, v85
	v_cvt_pk_bf16_f32 v69, v87, v89
	global_store_dwordx4 v[90:91], v[0:3], off nt
	global_store_dwordx4 v[92:93], v[4:7], off nt
	global_store_dwordx4 v[94:95], v[8:11], off nt
	v_lshl_add_u64 v[0:1], v[38:39], 0, v[14:15]
	global_store_dwordx4 v[0:1], v[66:69], off nt
	s_waitcnt lgkmcnt(0)

.LBB0_38:
	s_andn2_b64 vcc, exec, s[0:1]
	s_cbranch_vccnz .LBB0_40
	s_add_i32 s0, s47, 0xe380
	s_and_b32 s1, s0, 0xffff
	s_mul_i32 s1, s1, 0xba2f
	s_lshr_b32 s1, s1, 23
	s_mul_i32 s4, s1, 0xb0
	s_sub_i32 s4, s0, s4
	s_and_b32 s0, s4, 0xffff
	s_bfe_i32 s5, s4, 0x10002
	s_lshl_b32 s4, s4, 4
	s_lshl_b32 s0, s0, 5
	s_and_b32 s5, s5, 0xb00
	s_and_b32 s4, s4, 0xf80
	s_add_i32 s5, s5, s4
	s_and_b32 s4, s0, 0x60
	s_or_b32 s4, s5, s4
	v_or_b32_e32 v0, s4, v41
	s_lshl_b32 s28, s1, 6
	v_lshlrev_b32_e32 v14, 2, v0
	v_lshl_add_u64 v[38:39], s[78:79], 0, v[14:15]
	v_or_b32_e32 v4, s28, v12
	v_mad_u64_u32 v[0:1], s[4:5], v4, s44, v[38:39]
	v_lshlrev_b32_e32 v4, 2, v4
	v_or_b32_e32 v8, s28, v43
	global_load_dword v14, v4, s[84:85]
	v_mad_u64_u32 v[4:5], s[4:5], v8, s44, v[38:39]
	v_lshlrev_b32_e32 v8, 2, v8
	v_or_b32_e32 v65, s28, v45
	global_load_dword v86, v8, s[84:85]
	v_mad_u64_u32 v[8:9], s[4:5], v65, s44, v[38:39]
	v_lshlrev_b32_e32 v65, 2, v65
	global_load_dword v88, v65, s[84:85]
	v_or_b32_e32 v65, s28, v47
	v_mad_u64_u32 v[66:67], s[4:5], v65, s44, v[38:39]
	v_lshlrev_b32_e32 v65, 2, v65
	global_load_dword v90, v65, s[84:85]
	v_or_b32_e32 v65, s28, v48
	v_mad_u64_u32 v[70:71], s[4:5], v65, s44, v[38:39]
	v_lshlrev_b32_e32 v65, 2, v65
	global_load_dword v92, v65, s[84:85]
	v_or_b32_e32 v65, s28, v49
	v_mad_u64_u32 v[74:75], s[4:5], v65, s44, v[38:39]
	v_lshlrev_b32_e32 v65, 2, v65
	global_load_dword v94, v65, s[84:85]
	v_or_b32_e32 v65, s28, v50
	v_mad_u64_u32 v[78:79], s[4:5], v65, s44, v[38:39]
	v_lshlrev_b32_e32 v65, 2, v65
	global_load_dword v96, v65, s[84:85]
	v_or_b32_e32 v65, s28, v51
	global_load_dwordx4 v[0:3], v[0:1], off
	v_mad_u64_u32 v[38:39], s[4:5], v65, s44, v[38:39]
	global_load_dwordx4 v[4:7], v[4:5], off
	v_lshlrev_b32_e32 v65, 2, v65
	global_load_dwordx4 v[8:11], v[8:9], off
	v_add_u32_e32 v87, 0x18c8, v53
	global_load_dwordx4 v[66:69], v[66:67], off
	s_lshl_b32 s28, s1, 7
	global_load_dwordx4 v[70:73], v[70:71], off
	s_waitcnt vmcnt(4)
	v_pk_mul_f32 v[2:3], v[2:3], v[14:15] op_sel_hi:[1,0]
	global_load_dwordx4 v[74:77], v[74:75], off
	v_pk_mul_f32 v[0:1], v[0:1], v[14:15] op_sel_hi:[1,0]
	global_load_dwordx4 v[78:81], v[78:79], off
	s_nop 0
	global_load_dword v98, v65, s[84:85]
	global_load_dwordx4 v[82:85], v[38:39], off
	s_waitcnt vmcnt(7)
	v_pk_mul_f32 v[4:5], v[4:5], v[86:87] op_sel_hi:[1,0]
	v_add_u32_e32 v65, 0x18c0, v53
	v_pk_mul_f32 v[6:7], v[6:7], v[86:87] op_sel_hi:[1,0]
	s_waitcnt vmcnt(6)
	v_pk_mul_f32 v[10:11], v[10:11], v[88:89] op_sel_hi:[1,0]
	v_pk_mul_f32 v[8:9], v[8:9], v[88:89] op_sel_hi:[1,0]
	s_waitcnt vmcnt(5)
	v_pk_mul_f32 v[38:39], v[68:69], v[90:91] op_sel_hi:[1,0]
	v_pk_mul_f32 v[66:67], v[66:67], v[90:91] op_sel_hi:[1,0]
	s_waitcnt vmcnt(4)
	v_pk_mul_f32 v[68:69], v[72:73], v[92:93] op_sel_hi:[1,0]
	v_pk_mul_f32 v[70:71], v[70:71], v[92:93] op_sel_hi:[1,0]
	s_waitcnt vmcnt(3)
	v_pk_mul_f32 v[72:73], v[76:77], v[94:95] op_sel_hi:[1,0]
	v_pk_mul_f32 v[74:75], v[74:75], v[94:95] op_sel_hi:[1,0]
	s_waitcnt vmcnt(2)
	v_pk_mul_f32 v[76:77], v[80:81], v[96:97] op_sel_hi:[1,0]
	v_pk_mul_f32 v[78:79], v[78:79], v[96:97] op_sel_hi:[1,0]
	ds_write2_b32 v53, v0, v1 offset1:1
	ds_write2_b32 v53, v2, v3 offset0:2 offset1:3
	ds_write2_b32 v54, v4, v5 offset1:1
	ds_write2_b32 v55, v6, v7 offset1:1
	ds_write2_b32 v56, v8, v9 offset1:1
	ds_write2_b32 v57, v10, v11 offset1:1
	ds_write2_b32 v58, v66, v67 offset1:1
	ds_write2_b32 v59, v38, v39 offset1:1
	ds_write2_b32 v60, v70, v71 offset1:1
	ds_write2_b32 v61, v68, v69 offset1:1
	ds_write2_b32 v62, v74, v75 offset1:1
	ds_write2_b32 v63, v72, v73 offset1:1
	ds_write2_b32 v65, v78, v79 offset1:1
	ds_write2_b32 v87, v76, v77 offset1:1
	s_waitcnt vmcnt(0)
	v_pk_mul_f32 v[2:3], v[82:83], v[98:99] op_sel_hi:[1,0]
	v_add_u32_e32 v4, 0x1ce0, v53
	v_pk_mul_f32 v[0:1], v[84:85], v[98:99] op_sel_hi:[1,0]
	ds_write2_b32 v4, v2, v3 offset1:1
	v_add_u32_e32 v2, 0x1ce8, v53
	ds_write2_b32 v2, v0, v1 offset1:1
	s_waitcnt lgkmcnt(0)
	ds_read2_b32 v[4:5], v52 offset0:33 offset1:41
	ds_read2_b32 v[6:7], v52 offset1:8
	ds_read2_b32 v[8:9], v52 offset0:66 offset1:74
	ds_read2_b32 v[10:11], v52 offset0:99 offset1:107
	ds_read2_b32 v[38:39], v52 offset0:132 offset1:140
	ds_read2_b32 v[66:67], v52 offset0:165 offset1:173
	ds_read2_b32 v[68:69], v52 offset0:198 offset1:206
	ds_read2_b32 v[70:71], v52 offset0:231 offset1:239
	s_waitcnt lgkmcnt(6)
	v_cvt_pk_bf16_f32 v0, v6, v4
	v_or_b32_e32 v4, s0, v12
	v_lshl_add_u64 v[72:73], v[20:21], 0, s[28:29]
	v_lshlrev_b32_e32 v14, 11, v4
	s_waitcnt lgkmcnt(4)
	v_cvt_pk_bf16_f32 v1, v8, v10
	s_waitcnt lgkmcnt(2)
	v_cvt_pk_bf16_f32 v2, v38, v66
	s_waitcnt lgkmcnt(0)
	v_cvt_pk_bf16_f32 v3, v68, v70
	v_lshl_add_u64 v[74:75], v[72:73], 0, v[14:15]
	global_store_dwordx4 v[74:75], v[0:3], off nt
	v_or_b32_e32 v4, s0, v43
	v_lshlrev_b32_e32 v14, 11, v4
	v_cvt_pk_bf16_f32 v0, v7, v5
	v_cvt_pk_bf16_f32 v1, v9, v11
	v_cvt_pk_bf16_f32 v2, v39, v67
	v_cvt_pk_bf16_f32 v3, v69, v71
	ds_read2_b32 v[6:7], v52 offset0:49 offset1:57
	ds_read2_b32 v[8:9], v52 offset0:16 offset1:24
	ds_read2_b32 v[10:11], v52 offset0:82 offset1:90
	ds_read2_b32 v[38:39], v52 offset0:115 offset1:123
	ds_read2_b32 v[66:67], v52 offset0:148 offset1:156
	ds_read2_b32 v[68:69], v52 offset0:181 offset1:189
	ds_read2_b32 v[70:71], v52 offset0:214 offset1:222
	ds_read2_b32 v[74:75], v52 offset0:247 offset1:255
	v_lshl_add_u64 v[4:5], v[72:73], 0, v[14:15]
	global_store_dwordx4 v[4:5], v[0:3], off nt
	v_or_b32_e32 v4, s0, v45
	v_lshlrev_b32_e32 v14, 11, v4
	s_waitcnt lgkmcnt(6)
	v_cvt_pk_bf16_f32 v0, v8, v6
	s_waitcnt lgkmcnt(4)
	v_cvt_pk_bf16_f32 v1, v10, v38
	s_waitcnt lgkmcnt(2)
	v_cvt_pk_bf16_f32 v2, v66, v68
	s_waitcnt lgkmcnt(0)
	v_cvt_pk_bf16_f32 v3, v70, v74
	v_lshl_add_u64 v[4:5], v[72:73], 0, v[14:15]
	global_store_dwordx4 v[4:5], v[0:3], off nt
	v_or_b32_e32 v4, s0, v47
	v_lshlrev_b32_e32 v14, 11, v4
	v_cvt_pk_bf16_f32 v0, v9, v7
	v_cvt_pk_bf16_f32 v1, v11, v39
	v_cvt_pk_bf16_f32 v2, v67, v69
	v_cvt_pk_bf16_f32 v3, v71, v75
	v_lshl_add_u64 v[4:5], v[72:73], 0, v[14:15]
	global_store_dwordx4 v[4:5], v[0:3], off nt
	s_waitcnt lgkmcnt(0)

.Ltr_d_nogain:
	s_waitcnt vmcnt(0)
	ds_write2_b32 v53, v108, v109 offset1:1
	ds_write2_b32 v53, v110, v111 offset0:2 offset1:3
	v_add_u32_e32 v188, v42, v44
	ds_write2_b32 v188, v112, v113 offset1:1
	ds_write2_b32 v188, v114, v115 offset0:2 offset1:3
	v_add_u32_e32 v190, v42, v46
	ds_write2_b32 v190, v116, v117 offset1:1
	ds_write2_b32 v190, v118, v119 offset0:2 offset1:3
	v_add_u32_e32 v188, 0x420, v190
	ds_write2_b32 v188, v120, v121 offset1:1
	v_add_u32_e32 v189, 0x428, v190
	ds_write2_b32 v189, v122, v123 offset1:1
	v_add_u32_e32 v188, 0x840, v190
	ds_write2_b32 v188, v124, v125 offset1:1
	v_add_u32_e32 v189, 0x848, v190
	ds_write2_b32 v189, v126, v127 offset1:1
	v_add_u32_e32 v188, 0xc60, v190
	ds_write2_b32 v188, v128, v129 offset1:1
	v_add_u32_e32 v189, 0xc68, v190
	ds_write2_b32 v189, v130, v131 offset1:1
	v_add_u32_e32 v188, 0x1080, v190
	ds_write2_b32 v188, v132, v133 offset1:1
	v_add_u32_e32 v189, 0x1088, v190
	ds_write2_b32 v189, v134, v135 offset1:1
	v_add_u32_e32 v188, 0x14a0, v190
	ds_write2_b32 v188, v136, v137 offset1:1
	v_add_u32_e32 v189, 0x14a8, v190
	ds_write2_b32 v189, v138, v139 offset1:1
	s_waitcnt lgkmcnt(0)
	ds_read2_b32 v[4:5], v52 offset0:33 offset1:41
	ds_read2_b32 v[6:7], v52 offset1:8
	ds_read2_b32 v[8:9], v52 offset0:66 offset1:74
	ds_read2_b32 v[10:11], v52 offset0:99 offset1:107
	ds_read2_b32 v[38:39], v52 offset0:132 offset1:140
	ds_read2_b32 v[66:67], v52 offset0:165 offset1:173
	ds_read2_b32 v[68:69], v52 offset0:198 offset1:206
	ds_read2_b32 v[70:71], v52 offset0:231 offset1:239
	s_lshl_b32 s28, s5, 1
	s_waitcnt lgkmcnt(6)
	v_cvt_pk_bf16_f32 v0, v6, v4
	v_or_b32_e32 v4, s4, v12
	v_lshl_add_u64 v[72:73], v[22:23], 0, s[28:29]
	v_lshlrev_b32_e32 v14, 11, v4
	s_waitcnt lgkmcnt(4)
	v_cvt_pk_bf16_f32 v1, v8, v10
	s_waitcnt lgkmcnt(2)
	v_cvt_pk_bf16_f32 v2, v38, v66
	s_waitcnt lgkmcnt(0)
	v_cvt_pk_bf16_f32 v3, v68, v70
	v_lshl_add_u64 v[74:75], v[72:73], 0, v[14:15]
	global_store_dwordx4 v[74:75], v[0:3], off nt
	v_or_b32_e32 v4, s4, v43
	v_lshlrev_b32_e32 v14, 11, v4
	v_cvt_pk_bf16_f32 v0, v7, v5
	v_cvt_pk_bf16_f32 v1, v9, v11
	v_cvt_pk_bf16_f32 v2, v39, v67
	v_cvt_pk_bf16_f32 v3, v69, v71
	ds_read2_b32 v[6:7], v52 offset0:49 offset1:57
	ds_read2_b32 v[8:9], v52 offset0:16 offset1:24
	ds_read2_b32 v[10:11], v52 offset0:82 offset1:90
	ds_read2_b32 v[38:39], v52 offset0:115 offset1:123
	ds_read2_b32 v[66:67], v52 offset0:148 offset1:156
	ds_read2_b32 v[68:69], v52 offset0:181 offset1:189
	ds_read2_b32 v[70:71], v52 offset0:214 offset1:222
	ds_read2_b32 v[74:75], v52 offset0:247 offset1:255
	v_lshl_add_u64 v[4:5], v[72:73], 0, v[14:15]
	global_store_dwordx4 v[4:5], v[0:3], off nt
	v_or_b32_e32 v4, s4, v45
	v_lshlrev_b32_e32 v14, 11, v4
	s_waitcnt lgkmcnt(6)
	v_cvt_pk_bf16_f32 v0, v8, v6
	s_waitcnt lgkmcnt(4)
	v_cvt_pk_bf16_f32 v1, v10, v38
	s_waitcnt lgkmcnt(2)
	v_cvt_pk_bf16_f32 v2, v66, v68
	s_waitcnt lgkmcnt(0)
	v_cvt_pk_bf16_f32 v3, v70, v74
	v_lshl_add_u64 v[4:5], v[72:73], 0, v[14:15]
	global_store_dwordx4 v[4:5], v[0:3], off nt
	v_or_b32_e32 v4, s4, v47
	v_lshlrev_b32_e32 v14, 11, v4
	v_cvt_pk_bf16_f32 v0, v9, v7
	v_cvt_pk_bf16_f32 v1, v11, v39
	v_cvt_pk_bf16_f32 v2, v67, v69
	v_cvt_pk_bf16_f32 v3, v71, v75
	v_lshl_add_u64 v[4:5], v[72:73], 0, v[14:15]
	global_store_dwordx4 v[4:5], v[0:3], off nt
	s_waitcnt lgkmcnt(0)
	s_mov_b32 s30, s82

.LBB0_60:
	s_andn2_b64 vcc, exec, s[0:1]
	s_cbranch_vccnz .LBB0_62
	s_and_b32 s0, s38, 0x1e0
	s_and_b32 s1, s42, 0x3c0
	v_or_b32_e32 v0, s0, v41
	v_lshlrev_b32_e32 v14, 2, v0
	v_bitop3_b32 v0, s1, v12, v64 bitop3:0xde
	v_lshl_add_u64 v[38:39], s[94:95], 0, v[14:15]
	v_lshlrev_b32_e32 v14, 11, v0
	v_bitop3_b32 v2, s1, v43, v64 bitop3:0xde
	v_lshl_add_u64 v[0:1], v[38:39], 0, v[14:15]
	v_lshlrev_b32_e32 v14, 11, v2
	v_bitop3_b32 v8, s1, v45, v64 bitop3:0xde
	v_lshl_add_u64 v[4:5], v[38:39], 0, v[14:15]
	v_lshlrev_b32_e32 v14, 11, v8
	v_bitop3_b32 v10, s1, v47, v64 bitop3:0xde
	v_lshl_add_u64 v[8:9], v[38:39], 0, v[14:15]
	v_lshlrev_b32_e32 v14, 11, v10
	v_lshl_add_u64 v[66:67], v[38:39], 0, v[14:15]
	v_bitop3_b32 v14, s1, v48, v64 bitop3:0xde
	v_lshlrev_b32_e32 v14, 11, v14
	v_lshl_add_u64 v[70:71], v[38:39], 0, v[14:15]
	v_bitop3_b32 v14, s1, v49, v64 bitop3:0xde
	v_lshlrev_b32_e32 v14, 11, v14
	v_lshl_add_u64 v[74:75], v[38:39], 0, v[14:15]
	global_load_dwordx4 v[0:3], v[0:1], off
	s_nop 0
	global_load_dwordx4 v[4:7], v[4:5], off
	s_nop 0
	global_load_dwordx4 v[8:11], v[8:9], off
	s_nop 0
	global_load_dwordx4 v[66:69], v[66:67], off
	s_nop 0
	global_load_dwordx4 v[70:73], v[70:71], off
	s_nop 0
	global_load_dwordx4 v[74:77], v[74:75], off
	v_bitop3_b32 v14, s1, v50, v64 bitop3:0xde
	v_lshlrev_b32_e32 v14, 11, v14
	v_lshl_add_u64 v[78:79], v[38:39], 0, v[14:15]
	v_bitop3_b32 v14, s1, v51, v64 bitop3:0xde
	global_load_dwordx4 v[78:81], v[78:79], off
	v_lshlrev_b32_e32 v14, 11, v14
	v_lshl_add_u64 v[38:39], v[38:39], 0, v[14:15]
	global_load_dwordx4 v[82:85], v[38:39], off
	v_add_u32_e32 v65, 0x18c0, v53
	v_add_u32_e32 v92, 0x18c8, v53
	v_add_u32_e32 v93, 0x1ce0, v53
	v_add_u32_e32 v94, 0x1ce8, v53
	s_xor_b32 s1, s1, 0x200
	v_or_b32_e32 v14, s0, v12
	s_lshl_b32 s28, s1, 1
	v_or_b32_e32 v88, s0, v43
	v_lshl_add_u64 v[38:39], v[24:25], 0, s[28:29]
	v_lshlrev_b32_e32 v14, 11, v14
	v_or_b32_e32 v90, s0, v45
	v_lshl_add_u64 v[86:87], v[38:39], 0, v[14:15]
	v_lshlrev_b32_e32 v14, 11, v88
	v_lshl_add_u64 v[88:89], v[38:39], 0, v[14:15]
	v_lshlrev_b32_e32 v14, 11, v90
	v_lshl_add_u64 v[90:91], v[38:39], 0, v[14:15]
	s_waitcnt vmcnt(7)
	ds_write2_b32 v53, v0, v1 offset1:1
	ds_write2_b32 v53, v2, v3 offset0:2 offset1:3
	s_waitcnt vmcnt(6)
	ds_write2_b32 v54, v4, v5 offset1:1
	ds_write2_b32 v55, v6, v7 offset1:1
	s_waitcnt vmcnt(5)
	ds_write2_b32 v56, v8, v9 offset1:1
	ds_write2_b32 v57, v10, v11 offset1:1
	s_waitcnt vmcnt(4)
	ds_write2_b32 v58, v66, v67 offset1:1
	ds_write2_b32 v59, v68, v69 offset1:1
	s_waitcnt vmcnt(3)
	ds_write2_b32 v60, v70, v71 offset1:1
	ds_write2_b32 v61, v72, v73 offset1:1
	s_waitcnt vmcnt(2)
	ds_write2_b32 v62, v74, v75 offset1:1
	ds_write2_b32 v63, v76, v77 offset1:1
	s_waitcnt vmcnt(1)
	ds_write2_b32 v65, v78, v79 offset1:1
	ds_write2_b32 v92, v80, v81 offset1:1
	s_waitcnt vmcnt(0)
	ds_write2_b32 v93, v82, v83 offset1:1
	ds_write2_b32 v94, v84, v85 offset1:1
	s_waitcnt lgkmcnt(0)
	ds_read2_b32 v[4:5], v52 offset0:33 offset1:41
	ds_read2_b32 v[6:7], v52 offset1:8
	ds_read2_b32 v[8:9], v52 offset0:66 offset1:74
	ds_read2_b32 v[10:11], v52 offset0:99 offset1:107
	ds_read2_b32 v[66:67], v52 offset0:132 offset1:140
	ds_read2_b32 v[68:69], v52 offset0:165 offset1:173
	ds_read2_b32 v[70:71], v52 offset0:198 offset1:206
	ds_read2_b32 v[72:73], v52 offset0:231 offset1:239
	ds_read2_b32 v[74:75], v52 offset0:49 offset1:57
	ds_read2_b32 v[76:77], v52 offset0:16 offset1:24
	ds_read2_b32 v[78:79], v52 offset0:82 offset1:90
	ds_read2_b32 v[80:81], v52 offset0:115 offset1:123
	ds_read2_b32 v[82:83], v52 offset0:148 offset1:156
	ds_read2_b32 v[84:85], v52 offset0:181 offset1:189
	ds_read2_b32 v[92:93], v52 offset0:214 offset1:222
	ds_read2_b32 v[94:95], v52 offset0:247 offset1:255
	s_waitcnt lgkmcnt(14)
	v_cvt_pk_bf16_f32 v0, v6, v4
	s_waitcnt lgkmcnt(12)
	v_cvt_pk_bf16_f32 v1, v8, v10
	s_waitcnt lgkmcnt(10)
	v_cvt_pk_bf16_f32 v2, v66, v68
	s_waitcnt lgkmcnt(8)
	v_cvt_pk_bf16_f32 v3, v70, v72
	v_cvt_pk_bf16_f32 v4, v7, v5
	v_cvt_pk_bf16_f32 v5, v9, v11
	v_cvt_pk_bf16_f32 v6, v67, v69
	v_cvt_pk_bf16_f32 v7, v71, v73
	s_waitcnt lgkmcnt(6)
	v_cvt_pk_bf16_f32 v8, v76, v74
	s_waitcnt lgkmcnt(4)
	v_cvt_pk_bf16_f32 v9, v78, v80
	s_waitcnt lgkmcnt(2)
	v_cvt_pk_bf16_f32 v10, v82, v84
	s_waitcnt lgkmcnt(0)
	v_cvt_pk_bf16_f32 v11, v92, v94
	global_store_dwordx4 v[86:87], v[0:3], off nt
	global_store_dwordx4 v[88:89], v[4:7], off nt
	global_store_dwordx4 v[90:91], v[8:11], off nt
	v_cvt_pk_bf16_f32 v0, v77, v75
	v_or_b32_e32 v4, s0, v47
	v_lshlrev_b32_e32 v14, 11, v4
	v_cvt_pk_bf16_f32 v1, v79, v81
	v_cvt_pk_bf16_f32 v2, v83, v85
	v_cvt_pk_bf16_f32 v3, v93, v95
	v_lshl_add_u64 v[4:5], v[38:39], 0, v[14:15]
	global_store_dwordx4 v[4:5], v[0:3], off nt
	s_waitcnt lgkmcnt(0)

.LBB0_63:
	s_andn2_b64 vcc, exec, s[0:1]
	s_cbranch_vccnz .LBB0_65
	s_and_b32 s0, s38, 0x1e0
	s_and_b32 s1, s42, 0x3c0
	v_or_b32_e32 v0, s0, v41
	v_readlane_b32 s8, v250, 13
	v_lshlrev_b32_e32 v14, 2, v0
	v_readlane_b32 s22, v250, 27
	v_readlane_b32 s23, v250, 28
	v_bitop3_b32 v0, s1, v12, v64 bitop3:0xde
	v_bitop3_b32 v2, s1, v43, v64 bitop3:0xde
	v_lshl_add_u64 v[38:39], s[22:23], 0, v[14:15]
	v_lshlrev_b32_e32 v14, 11, v0
	v_lshl_add_u64 v[0:1], v[38:39], 0, v[14:15]
	v_lshlrev_b32_e32 v14, 11, v2
	v_bitop3_b32 v8, s1, v45, v64 bitop3:0xde
	v_lshl_add_u64 v[4:5], v[38:39], 0, v[14:15]
	v_lshlrev_b32_e32 v14, 11, v8
	v_bitop3_b32 v10, s1, v47, v64 bitop3:0xde
	v_lshl_add_u64 v[8:9], v[38:39], 0, v[14:15]
	v_lshlrev_b32_e32 v14, 11, v10
	v_lshl_add_u64 v[66:67], v[38:39], 0, v[14:15]
	v_bitop3_b32 v14, s1, v48, v64 bitop3:0xde
	v_lshlrev_b32_e32 v14, 11, v14
	v_lshl_add_u64 v[70:71], v[38:39], 0, v[14:15]
	v_bitop3_b32 v14, s1, v49, v64 bitop3:0xde
	v_lshlrev_b32_e32 v14, 11, v14
	v_lshl_add_u64 v[74:75], v[38:39], 0, v[14:15]
	global_load_dwordx4 v[0:3], v[0:1], off
	s_nop 0
	global_load_dwordx4 v[4:7], v[4:5], off
	s_nop 0
	global_load_dwordx4 v[8:11], v[8:9], off
	s_nop 0
	global_load_dwordx4 v[66:69], v[66:67], off
	s_nop 0
	global_load_dwordx4 v[70:73], v[70:71], off
	s_nop 0
	global_load_dwordx4 v[74:77], v[74:75], off
	v_bitop3_b32 v14, s1, v50, v64 bitop3:0xde
	v_lshlrev_b32_e32 v14, 11, v14
	v_lshl_add_u64 v[78:79], v[38:39], 0, v[14:15]
	v_bitop3_b32 v14, s1, v51, v64 bitop3:0xde
	global_load_dwordx4 v[78:81], v[78:79], off
	v_lshlrev_b32_e32 v14, 11, v14
	v_lshl_add_u64 v[38:39], v[38:39], 0, v[14:15]
	global_load_dwordx4 v[82:85], v[38:39], off
	v_add_u32_e32 v65, 0x18c0, v53
	v_add_u32_e32 v92, 0x18c8, v53
	v_add_u32_e32 v93, 0x1ce0, v53
	v_add_u32_e32 v94, 0x1ce8, v53
	s_xor_b32 s1, s1, 0x200
	v_or_b32_e32 v14, s0, v12
	s_lshl_b32 s28, s1, 1
	v_or_b32_e32 v88, s0, v43
	v_lshl_add_u64 v[38:39], v[26:27], 0, s[28:29]
	v_lshlrev_b32_e32 v14, 11, v14
	v_or_b32_e32 v90, s0, v45
	v_lshl_add_u64 v[86:87], v[38:39], 0, v[14:15]
	v_lshlrev_b32_e32 v14, 11, v88
	v_lshl_add_u64 v[88:89], v[38:39], 0, v[14:15]
	v_lshlrev_b32_e32 v14, 11, v90
	v_lshl_add_u64 v[90:91], v[38:39], 0, v[14:15]
	v_readlane_b32 s9, v250, 14
	v_readlane_b32 s10, v250, 15
	v_readlane_b32 s11, v250, 16
	v_readlane_b32 s12, v250, 17
	v_readlane_b32 s13, v250, 18
	v_readlane_b32 s14, v250, 19
	v_readlane_b32 s15, v250, 20
	v_readlane_b32 s16, v250, 21
	v_readlane_b32 s17, v250, 22
	v_readlane_b32 s18, v250, 23
	v_readlane_b32 s19, v250, 24
	v_readlane_b32 s20, v250, 25
	v_readlane_b32 s21, v250, 26
	s_waitcnt vmcnt(7)
	ds_write2_b32 v53, v0, v1 offset1:1
	ds_write2_b32 v53, v2, v3 offset0:2 offset1:3
	s_waitcnt vmcnt(6)
	ds_write2_b32 v54, v4, v5 offset1:1
	ds_write2_b32 v55, v6, v7 offset1:1
	s_waitcnt vmcnt(5)
	ds_write2_b32 v56, v8, v9 offset1:1
	ds_write2_b32 v57, v10, v11 offset1:1
	s_waitcnt vmcnt(4)
	ds_write2_b32 v58, v66, v67 offset1:1
	ds_write2_b32 v59, v68, v69 offset1:1
	s_waitcnt vmcnt(3)
	ds_write2_b32 v60, v70, v71 offset1:1
	ds_write2_b32 v61, v72, v73 offset1:1
	s_waitcnt vmcnt(2)
	ds_write2_b32 v62, v74, v75 offset1:1
	ds_write2_b32 v63, v76, v77 offset1:1
	s_waitcnt vmcnt(1)
	ds_write2_b32 v65, v78, v79 offset1:1
	ds_write2_b32 v92, v80, v81 offset1:1
	s_waitcnt vmcnt(0)
	ds_write2_b32 v93, v82, v83 offset1:1
	ds_write2_b32 v94, v84, v85 offset1:1
	s_waitcnt lgkmcnt(0)
	ds_read2_b32 v[4:5], v52 offset0:33 offset1:41
	ds_read2_b32 v[6:7], v52 offset1:8
	ds_read2_b32 v[8:9], v52 offset0:66 offset1:74
	ds_read2_b32 v[10:11], v52 offset0:99 offset1:107
	ds_read2_b32 v[66:67], v52 offset0:132 offset1:140
	ds_read2_b32 v[68:69], v52 offset0:165 offset1:173
	ds_read2_b32 v[70:71], v52 offset0:198 offset1:206
	ds_read2_b32 v[72:73], v52 offset0:231 offset1:239
	ds_read2_b32 v[74:75], v52 offset0:49 offset1:57
	ds_read2_b32 v[76:77], v52 offset0:16 offset1:24
	ds_read2_b32 v[78:79], v52 offset0:82 offset1:90
	ds_read2_b32 v[80:81], v52 offset0:115 offset1:123
	ds_read2_b32 v[82:83], v52 offset0:148 offset1:156
	ds_read2_b32 v[84:85], v52 offset0:181 offset1:189
	ds_read2_b32 v[92:93], v52 offset0:214 offset1:222
	ds_read2_b32 v[94:95], v52 offset0:247 offset1:255
	s_waitcnt lgkmcnt(14)
	v_cvt_pk_bf16_f32 v0, v6, v4
	s_waitcnt lgkmcnt(12)
	v_cvt_pk_bf16_f32 v1, v8, v10
	s_waitcnt lgkmcnt(10)
	v_cvt_pk_bf16_f32 v2, v66, v68
	s_waitcnt lgkmcnt(8)
	v_cvt_pk_bf16_f32 v3, v70, v72
	v_cvt_pk_bf16_f32 v4, v7, v5
	v_cvt_pk_bf16_f32 v5, v9, v11
	v_cvt_pk_bf16_f32 v6, v67, v69
	v_cvt_pk_bf16_f32 v7, v71, v73
	s_waitcnt lgkmcnt(6)
	v_cvt_pk_bf16_f32 v8, v76, v74
	s_waitcnt lgkmcnt(4)
	v_cvt_pk_bf16_f32 v9, v78, v80
	s_waitcnt lgkmcnt(2)
	v_cvt_pk_bf16_f32 v10, v82, v84
	s_waitcnt lgkmcnt(0)
	v_cvt_pk_bf16_f32 v11, v92, v94
	global_store_dwordx4 v[86:87], v[0:3], off nt
	global_store_dwordx4 v[88:89], v[4:7], off nt
	global_store_dwordx4 v[90:91], v[8:11], off nt
	v_cvt_pk_bf16_f32 v0, v77, v75
	v_or_b32_e32 v4, s0, v47
	v_lshlrev_b32_e32 v14, 11, v4
	v_cvt_pk_bf16_f32 v1, v79, v81
	v_cvt_pk_bf16_f32 v2, v83, v85
	v_cvt_pk_bf16_f32 v3, v93, v95
	v_lshl_add_u64 v[4:5], v[38:39], 0, v[14:15]
	global_store_dwordx4 v[4:5], v[0:3], off nt
	s_waitcnt lgkmcnt(0)

.LBB0_66:
	s_andn2_b64 vcc, exec, s[0:1]
	s_cbranch_vccnz .LBB0_68
	s_add_i32 s0, s40, 0x3f00
	s_and_b32 s1, s0, 0x1ffc0
	s_and_b32 s0, s38, 0x3e0
	v_or_b32_e32 v0, s0, v41
	v_readlane_b32 s8, v250, 13
	v_lshlrev_b32_e32 v14, 2, v0
	v_readlane_b32 s20, v250, 25
	v_readlane_b32 s21, v250, 26
	v_or_b32_e32 v0, s1, v12
	v_or_b32_e32 v2, s1, v43
	v_lshl_add_u64 v[38:39], s[20:21], 0, v[14:15]
	v_lshlrev_b32_e32 v14, 12, v0
	v_lshl_add_u64 v[0:1], v[38:39], 0, v[14:15]
	v_lshlrev_b32_e32 v14, 12, v2
	v_or_b32_e32 v8, s1, v45
	v_lshl_add_u64 v[4:5], v[38:39], 0, v[14:15]
	v_lshlrev_b32_e32 v14, 12, v8
	v_or_b32_e32 v10, s1, v47
	v_lshl_add_u64 v[8:9], v[38:39], 0, v[14:15]
	v_lshlrev_b32_e32 v14, 12, v10
	v_lshl_add_u64 v[66:67], v[38:39], 0, v[14:15]
	v_or_b32_e32 v14, s1, v48
	v_lshlrev_b32_e32 v14, 12, v14
	v_lshl_add_u64 v[70:71], v[38:39], 0, v[14:15]
	v_or_b32_e32 v14, s1, v49
	v_lshlrev_b32_e32 v14, 12, v14
	v_lshl_add_u64 v[74:75], v[38:39], 0, v[14:15]
	global_load_dwordx4 v[0:3], v[0:1], off
	s_nop 0
	global_load_dwordx4 v[4:7], v[4:5], off
	s_nop 0
	global_load_dwordx4 v[8:11], v[8:9], off
	s_nop 0
	global_load_dwordx4 v[66:69], v[66:67], off
	s_nop 0
	global_load_dwordx4 v[70:73], v[70:71], off
	s_nop 0
	global_load_dwordx4 v[74:77], v[74:75], off
	v_or_b32_e32 v14, s1, v50
	v_lshlrev_b32_e32 v14, 12, v14
	v_lshl_add_u64 v[78:79], v[38:39], 0, v[14:15]
	v_or_b32_e32 v14, s1, v51
	global_load_dwordx4 v[78:81], v[78:79], off
	v_lshlrev_b32_e32 v14, 12, v14
	v_lshl_add_u64 v[38:39], v[38:39], 0, v[14:15]
	global_load_dwordx4 v[82:85], v[38:39], off
	v_add_u32_e32 v65, 0x18c0, v53
	v_add_u32_e32 v92, 0x18c8, v53
	v_add_u32_e32 v93, 0x1ce0, v53
	v_add_u32_e32 v94, 0x1ce8, v53
	v_or_b32_e32 v14, s0, v12
	s_lshl_b32 s28, s1, 1
	v_or_b32_e32 v88, s0, v43
	v_lshl_add_u64 v[38:39], v[28:29], 0, s[28:29]
	v_lshlrev_b32_e32 v14, 11, v14
	v_or_b32_e32 v90, s0, v45
	v_lshl_add_u64 v[86:87], v[38:39], 0, v[14:15]
	v_lshlrev_b32_e32 v14, 11, v88
	v_lshl_add_u64 v[88:89], v[38:39], 0, v[14:15]
	v_lshlrev_b32_e32 v14, 11, v90
	v_lshl_add_u64 v[90:91], v[38:39], 0, v[14:15]
	v_readlane_b32 s9, v250, 14
	v_readlane_b32 s10, v250, 15
	v_readlane_b32 s11, v250, 16
	v_readlane_b32 s12, v250, 17
	v_readlane_b32 s13, v250, 18
	v_readlane_b32 s14, v250, 19
	v_readlane_b32 s15, v250, 20
	v_readlane_b32 s16, v250, 21
	v_readlane_b32 s17, v250, 22
	v_readlane_b32 s18, v250, 23
	v_readlane_b32 s19, v250, 24
	v_readlane_b32 s22, v250, 27
	v_readlane_b32 s23, v250, 28
	s_waitcnt vmcnt(7)
	ds_write2_b32 v53, v0, v1 offset1:1
	ds_write2_b32 v53, v2, v3 offset0:2 offset1:3
	s_waitcnt vmcnt(6)
	ds_write2_b32 v54, v4, v5 offset1:1
	ds_write2_b32 v55, v6, v7 offset1:1
	s_waitcnt vmcnt(5)
	ds_write2_b32 v56, v8, v9 offset1:1
	ds_write2_b32 v57, v10, v11 offset1:1
	s_waitcnt vmcnt(4)
	ds_write2_b32 v58, v66, v67 offset1:1
	ds_write2_b32 v59, v68, v69 offset1:1
	s_waitcnt vmcnt(3)
	ds_write2_b32 v60, v70, v71 offset1:1
	ds_write2_b32 v61, v72, v73 offset1:1
	s_waitcnt vmcnt(2)
	ds_write2_b32 v62, v74, v75 offset1:1
	ds_write2_b32 v63, v76, v77 offset1:1
	s_waitcnt vmcnt(1)
	ds_write2_b32 v65, v78, v79 offset1:1
	ds_write2_b32 v92, v80, v81 offset1:1
	s_waitcnt vmcnt(0)
	ds_write2_b32 v93, v82, v83 offset1:1
	ds_write2_b32 v94, v84, v85 offset1:1
	s_waitcnt lgkmcnt(0)
	ds_read2_b32 v[4:5], v52 offset0:33 offset1:41
	ds_read2_b32 v[6:7], v52 offset1:8
	ds_read2_b32 v[8:9], v52 offset0:66 offset1:74
	ds_read2_b32 v[10:11], v52 offset0:99 offset1:107
	ds_read2_b32 v[66:67], v52 offset0:132 offset1:140
	ds_read2_b32 v[68:69], v52 offset0:165 offset1:173
	ds_read2_b32 v[70:71], v52 offset0:198 offset1:206
	ds_read2_b32 v[72:73], v52 offset0:231 offset1:239
	ds_read2_b32 v[74:75], v52 offset0:49 offset1:57
	ds_read2_b32 v[76:77], v52 offset0:16 offset1:24
	ds_read2_b32 v[78:79], v52 offset0:82 offset1:90
	ds_read2_b32 v[80:81], v52 offset0:115 offset1:123
	ds_read2_b32 v[82:83], v52 offset0:148 offset1:156
	ds_read2_b32 v[84:85], v52 offset0:181 offset1:189
	ds_read2_b32 v[92:93], v52 offset0:214 offset1:222
	ds_read2_b32 v[94:95], v52 offset0:247 offset1:255
	s_waitcnt lgkmcnt(14)
	v_cvt_pk_bf16_f32 v0, v6, v4
	s_waitcnt lgkmcnt(12)
	v_cvt_pk_bf16_f32 v1, v8, v10
	s_waitcnt lgkmcnt(10)
	v_cvt_pk_bf16_f32 v2, v66, v68
	s_waitcnt lgkmcnt(8)
	v_cvt_pk_bf16_f32 v3, v70, v72
	v_cvt_pk_bf16_f32 v4, v7, v5
	v_cvt_pk_bf16_f32 v5, v9, v11
	v_cvt_pk_bf16_f32 v6, v67, v69
	v_cvt_pk_bf16_f32 v7, v71, v73
	s_waitcnt lgkmcnt(6)
	v_cvt_pk_bf16_f32 v8, v76, v74
	s_waitcnt lgkmcnt(4)
	v_cvt_pk_bf16_f32 v9, v78, v80
	s_waitcnt lgkmcnt(2)
	v_cvt_pk_bf16_f32 v10, v82, v84
	s_waitcnt lgkmcnt(0)
	v_cvt_pk_bf16_f32 v11, v92, v94
	global_store_dwordx4 v[86:87], v[0:3], off nt
	global_store_dwordx4 v[88:89], v[4:7], off nt
	global_store_dwordx4 v[90:91], v[8:11], off nt
	v_cvt_pk_bf16_f32 v0, v77, v75
	v_or_b32_e32 v4, s0, v47
	v_lshlrev_b32_e32 v14, 11, v4
	v_cvt_pk_bf16_f32 v1, v79, v81
	v_cvt_pk_bf16_f32 v2, v83, v85
	v_cvt_pk_bf16_f32 v3, v93, v95
	v_lshl_add_u64 v[4:5], v[38:39], 0, v[14:15]
	global_store_dwordx4 v[4:5], v[0:3], off nt
	s_waitcnt lgkmcnt(0)

.Ltr_h_nogain:
	s_waitcnt vmcnt(0)
	ds_write2_b32 v53, v108, v109 offset1:1
	ds_write2_b32 v53, v110, v111 offset0:2 offset1:3
	v_add_u32_e32 v188, v42, v44
	ds_write2_b32 v188, v112, v113 offset1:1
	ds_write2_b32 v188, v114, v115 offset0:2 offset1:3
	v_add_u32_e32 v190, v42, v46
	ds_write2_b32 v190, v116, v117 offset1:1
	ds_write2_b32 v190, v118, v119 offset0:2 offset1:3
	v_add_u32_e32 v188, 0x420, v190
	ds_write2_b32 v188, v120, v121 offset1:1
	v_add_u32_e32 v189, 0x428, v190
	ds_write2_b32 v189, v122, v123 offset1:1
	v_add_u32_e32 v188, 0x840, v190
	ds_write2_b32 v188, v124, v125 offset1:1
	v_add_u32_e32 v189, 0x848, v190
	ds_write2_b32 v189, v126, v127 offset1:1
	v_add_u32_e32 v188, 0xc60, v190
	ds_write2_b32 v188, v128, v129 offset1:1
	v_add_u32_e32 v189, 0xc68, v190
	ds_write2_b32 v189, v130, v131 offset1:1
	v_add_u32_e32 v188, 0x1080, v190
	ds_write2_b32 v188, v132, v133 offset1:1
	v_add_u32_e32 v189, 0x1088, v190
	ds_write2_b32 v189, v134, v135 offset1:1
	v_add_u32_e32 v188, 0x14a0, v190
	ds_write2_b32 v188, v136, v137 offset1:1
	v_add_u32_e32 v189, 0x14a8, v190
	ds_write2_b32 v189, v138, v139 offset1:1
	s_waitcnt lgkmcnt(0)
	ds_read2_b32 v[4:5], v52 offset0:33 offset1:41
	ds_read2_b32 v[6:7], v52 offset1:8
	ds_read2_b32 v[8:9], v52 offset0:66 offset1:74
	ds_read2_b32 v[10:11], v52 offset0:99 offset1:107
	ds_read2_b32 v[38:39], v52 offset0:132 offset1:140
	ds_read2_b32 v[66:67], v52 offset0:165 offset1:173
	ds_read2_b32 v[68:69], v52 offset0:198 offset1:206
	ds_read2_b32 v[70:71], v52 offset0:231 offset1:239
	s_lshl_b32 s28, s5, 1
	s_waitcnt lgkmcnt(6)
	v_cvt_pk_bf16_f32 v0, v6, v4
	v_or_b32_e32 v4, s4, v12
	v_lshl_add_u64 v[72:73], v[30:31], 0, s[28:29]
	v_lshlrev_b32_e32 v14, 11, v4
	s_waitcnt lgkmcnt(4)
	v_cvt_pk_bf16_f32 v1, v8, v10
	s_waitcnt lgkmcnt(2)
	v_cvt_pk_bf16_f32 v2, v38, v66
	s_waitcnt lgkmcnt(0)
	v_cvt_pk_bf16_f32 v3, v68, v70
	v_lshl_add_u64 v[74:75], v[72:73], 0, v[14:15]
	global_store_dwordx4 v[74:75], v[0:3], off nt
	v_or_b32_e32 v4, s4, v43
	v_lshlrev_b32_e32 v14, 11, v4
	v_cvt_pk_bf16_f32 v0, v7, v5
	v_cvt_pk_bf16_f32 v1, v9, v11
	v_cvt_pk_bf16_f32 v2, v39, v67
	v_cvt_pk_bf16_f32 v3, v69, v71
	ds_read2_b32 v[6:7], v52 offset0:49 offset1:57
	ds_read2_b32 v[8:9], v52 offset0:16 offset1:24
	ds_read2_b32 v[10:11], v52 offset0:82 offset1:90
	ds_read2_b32 v[38:39], v52 offset0:115 offset1:123
	ds_read2_b32 v[66:67], v52 offset0:148 offset1:156
	ds_read2_b32 v[68:69], v52 offset0:181 offset1:189
	ds_read2_b32 v[70:71], v52 offset0:214 offset1:222
	ds_read2_b32 v[74:75], v52 offset0:247 offset1:255
	v_lshl_add_u64 v[4:5], v[72:73], 0, v[14:15]
	global_store_dwordx4 v[4:5], v[0:3], off nt
	v_or_b32_e32 v4, s4, v45
	v_lshlrev_b32_e32 v14, 11, v4
	s_waitcnt lgkmcnt(6)
	v_cvt_pk_bf16_f32 v0, v8, v6
	s_waitcnt lgkmcnt(4)
	v_cvt_pk_bf16_f32 v1, v10, v38
	s_waitcnt lgkmcnt(2)
	v_cvt_pk_bf16_f32 v2, v66, v68
	s_waitcnt lgkmcnt(0)
	v_cvt_pk_bf16_f32 v3, v70, v74
	v_lshl_add_u64 v[4:5], v[72:73], 0, v[14:15]
	global_store_dwordx4 v[4:5], v[0:3], off nt
	v_or_b32_e32 v4, s4, v47
	v_lshlrev_b32_e32 v14, 11, v4
	v_cvt_pk_bf16_f32 v0, v9, v7
	v_cvt_pk_bf16_f32 v1, v11, v39
	v_cvt_pk_bf16_f32 v2, v67, v69
	v_cvt_pk_bf16_f32 v3, v71, v75
	v_lshl_add_u64 v[4:5], v[72:73], 0, v[14:15]
	global_store_dwordx4 v[4:5], v[0:3], off nt
	s_waitcnt lgkmcnt(0)

.LBB0_89:
	s_andn2_b64 vcc, exec, s[0:1]
	s_cbranch_vccnz .LBB0_91
	s_add_i32 s0, s40, 0x4900
	s_and_b32 s1, s0, 0x1ffc0
	s_and_b32 s0, s38, 0x3e0
	v_or_b32_e32 v0, s0, v41
	v_readlane_b32 s8, v250, 13
	v_lshlrev_b32_e32 v14, 2, v0
	v_readlane_b32 s16, v250, 21
	v_readlane_b32 s17, v250, 22
	v_or_b32_e32 v4, s1, v12
	v_or_b32_e32 v8, s1, v43
	v_lshl_add_u64 v[38:39], s[16:17], 0, v[14:15]
	v_lshlrev_b32_e32 v14, 12, v4
	v_lshl_add_u64 v[0:1], v[38:39], 0, v[14:15]
	v_lshlrev_b32_e32 v4, 2, v4
	v_lshlrev_b32_e32 v14, 12, v8
	v_lshlrev_b32_e32 v8, 2, v8
	v_or_b32_e32 v65, s1, v45
	global_load_dword v86, v4, s[24:25]
	global_load_dword v88, v8, s[24:25]
	v_lshl_add_u64 v[4:5], v[38:39], 0, v[14:15]
	v_lshlrev_b32_e32 v14, 12, v65
	v_lshl_add_u64 v[8:9], v[38:39], 0, v[14:15]
	v_lshlrev_b32_e32 v14, 2, v65
	v_or_b32_e32 v65, s1, v47
	global_load_dword v90, v14, s[24:25]
	v_lshlrev_b32_e32 v14, 12, v65
	v_lshl_add_u64 v[66:67], v[38:39], 0, v[14:15]
	v_lshlrev_b32_e32 v14, 2, v65
	v_or_b32_e32 v65, s1, v48
	global_load_dword v92, v14, s[24:25]
	v_lshlrev_b32_e32 v14, 12, v65
	global_load_dwordx4 v[0:3], v[0:1], off
	v_lshl_add_u64 v[70:71], v[38:39], 0, v[14:15]
	v_lshlrev_b32_e32 v14, 2, v65
	v_or_b32_e32 v65, s1, v49
	global_load_dwordx4 v[4:7], v[4:5], off
	v_add_u32_e32 v87, 0x1ce8, v53
	global_load_dword v94, v14, s[24:25]
	v_lshlrev_b32_e32 v14, 12, v65
	global_load_dwordx4 v[8:11], v[8:9], off
	v_lshl_add_u64 v[74:75], v[38:39], 0, v[14:15]
	v_lshlrev_b32_e32 v14, 2, v65
	v_or_b32_e32 v65, s1, v50
	global_load_dwordx4 v[66:69], v[66:67], off
	s_lshl_b32 s28, s1, 1
	global_load_dword v96, v14, s[24:25]
	v_lshlrev_b32_e32 v14, 12, v65
	global_load_dwordx4 v[70:73], v[70:71], off
	v_lshl_add_u64 v[78:79], v[38:39], 0, v[14:15]
	v_lshlrev_b32_e32 v14, 2, v65
	v_or_b32_e32 v65, s1, v51
	global_load_dwordx4 v[74:77], v[74:75], off
	v_readlane_b32 s9, v250, 14
	global_load_dword v98, v14, s[24:25]
	v_lshlrev_b32_e32 v14, 12, v65
	global_load_dwordx4 v[78:81], v[78:79], off
	v_lshl_add_u64 v[38:39], v[38:39], 0, v[14:15]
	v_lshlrev_b32_e32 v14, 2, v65
	global_load_dword v14, v14, s[24:25]
	s_nop 0
	global_load_dwordx4 v[82:85], v[38:39], off
	v_add_u32_e32 v38, 0x18c0, v53
	v_add_u32_e32 v39, 0x18c8, v53
	v_add_u32_e32 v65, 0x1ce0, v53
	v_readlane_b32 s10, v250, 15
	v_readlane_b32 s11, v250, 16
	v_readlane_b32 s12, v250, 17
	v_readlane_b32 s13, v250, 18
	v_readlane_b32 s14, v250, 19
	v_readlane_b32 s15, v250, 20
	v_readlane_b32 s18, v250, 23
	v_readlane_b32 s19, v250, 24
	v_readlane_b32 s20, v250, 25
	v_readlane_b32 s21, v250, 26
	v_readlane_b32 s22, v250, 27
	v_readlane_b32 s23, v250, 28
	s_waitcnt vmcnt(11)
	v_pk_mul_f32 v[2:3], v[2:3], v[86:87] op_sel_hi:[1,0]
	v_pk_mul_f32 v[0:1], v[0:1], v[86:87] op_sel_hi:[1,0]
	ds_write2_b32 v53, v0, v1 offset1:1
	ds_write2_b32 v53, v2, v3 offset0:2 offset1:3
	s_waitcnt vmcnt(10)
	v_pk_mul_f32 v[2:3], v[4:5], v[88:89] op_sel_hi:[1,0]
	v_pk_mul_f32 v[0:1], v[6:7], v[88:89] op_sel_hi:[1,0]
	ds_write2_b32 v54, v2, v3 offset1:1
	ds_write2_b32 v55, v0, v1 offset1:1
	s_waitcnt vmcnt(8)
	v_pk_mul_f32 v[2:3], v[8:9], v[90:91] op_sel_hi:[1,0]
	v_pk_mul_f32 v[0:1], v[10:11], v[90:91] op_sel_hi:[1,0]
	ds_write2_b32 v56, v2, v3 offset1:1
	ds_write2_b32 v57, v0, v1 offset1:1
	s_waitcnt vmcnt(7)
	v_pk_mul_f32 v[2:3], v[66:67], v[92:93] op_sel_hi:[1,0]
	v_pk_mul_f32 v[0:1], v[68:69], v[92:93] op_sel_hi:[1,0]
	ds_write2_b32 v58, v2, v3 offset1:1
	ds_write2_b32 v59, v0, v1 offset1:1
	s_waitcnt vmcnt(5)
	v_pk_mul_f32 v[2:3], v[70:71], v[94:95] op_sel_hi:[1,0]
	v_pk_mul_f32 v[0:1], v[72:73], v[94:95] op_sel_hi:[1,0]
	ds_write2_b32 v60, v2, v3 offset1:1
	ds_write2_b32 v61, v0, v1 offset1:1
	v_lshl_add_u64 v[72:73], v[32:33], 0, s[28:29]
	s_waitcnt vmcnt(4)
	v_pk_mul_f32 v[2:3], v[74:75], v[96:97] op_sel_hi:[1,0]
	v_pk_mul_f32 v[0:1], v[76:77], v[96:97] op_sel_hi:[1,0]
	ds_write2_b32 v62, v2, v3 offset1:1
	ds_write2_b32 v63, v0, v1 offset1:1
	s_waitcnt vmcnt(2)
	v_pk_mul_f32 v[2:3], v[78:79], v[98:99] op_sel_hi:[1,0]
	v_pk_mul_f32 v[0:1], v[80:81], v[98:99] op_sel_hi:[1,0]
	ds_write2_b32 v38, v2, v3 offset1:1
	ds_write2_b32 v39, v0, v1 offset1:1
	s_waitcnt vmcnt(0)
	v_pk_mul_f32 v[2:3], v[82:83], v[14:15] op_sel_hi:[1,0]
	v_pk_mul_f32 v[0:1], v[84:85], v[14:15] op_sel_hi:[1,0]
	ds_write2_b32 v65, v2, v3 offset1:1
	ds_write2_b32 v87, v0, v1 offset1:1
	s_waitcnt lgkmcnt(0)
	ds_read2_b32 v[4:5], v52 offset0:33 offset1:41
	ds_read2_b32 v[6:7], v52 offset1:8
	ds_read2_b32 v[8:9], v52 offset0:66 offset1:74
	ds_read2_b32 v[10:11], v52 offset0:99 offset1:107
	ds_read2_b32 v[38:39], v52 offset0:132 offset1:140
	ds_read2_b32 v[66:67], v52 offset0:165 offset1:173
	ds_read2_b32 v[68:69], v52 offset0:198 offset1:206
	ds_read2_b32 v[70:71], v52 offset0:231 offset1:239
	s_waitcnt lgkmcnt(6)
	v_cvt_pk_bf16_f32 v0, v6, v4
	v_or_b32_e32 v4, s0, v12
	v_lshlrev_b32_e32 v14, 11, v4
	s_waitcnt lgkmcnt(4)
	v_cvt_pk_bf16_f32 v1, v8, v10
	s_waitcnt lgkmcnt(2)
	v_cvt_pk_bf16_f32 v2, v38, v66
	s_waitcnt lgkmcnt(0)
	v_cvt_pk_bf16_f32 v3, v68, v70
	v_lshl_add_u64 v[74:75], v[72:73], 0, v[14:15]
	global_store_dwordx4 v[74:75], v[0:3], off nt
	v_or_b32_e32 v4, s0, v43
	v_lshlrev_b32_e32 v14, 11, v4
	v_cvt_pk_bf16_f32 v0, v7, v5
	v_cvt_pk_bf16_f32 v1, v9, v11
	v_cvt_pk_bf16_f32 v2, v39, v67
	v_cvt_pk_bf16_f32 v3, v69, v71
	ds_read2_b32 v[6:7], v52 offset0:49 offset1:57
	ds_read2_b32 v[8:9], v52 offset0:16 offset1:24
	ds_read2_b32 v[10:11], v52 offset0:82 offset1:90
	ds_read2_b32 v[38:39], v52 offset0:115 offset1:123
	ds_read2_b32 v[66:67], v52 offset0:148 offset1:156
	ds_read2_b32 v[68:69], v52 offset0:181 offset1:189
	ds_read2_b32 v[70:71], v52 offset0:214 offset1:222
	ds_read2_b32 v[74:75], v52 offset0:247 offset1:255
	v_lshl_add_u64 v[4:5], v[72:73], 0, v[14:15]
	global_store_dwordx4 v[4:5], v[0:3], off nt
	v_or_b32_e32 v4, s0, v45
	v_lshlrev_b32_e32 v14, 11, v4
	s_waitcnt lgkmcnt(6)
	v_cvt_pk_bf16_f32 v0, v8, v6
	s_waitcnt lgkmcnt(4)
	v_cvt_pk_bf16_f32 v1, v10, v38
	s_waitcnt lgkmcnt(2)
	v_cvt_pk_bf16_f32 v2, v66, v68
	s_waitcnt lgkmcnt(0)
	v_cvt_pk_bf16_f32 v3, v70, v74
	v_lshl_add_u64 v[4:5], v[72:73], 0, v[14:15]
	global_store_dwordx4 v[4:5], v[0:3], off nt
	v_or_b32_e32 v4, s0, v47
	v_lshlrev_b32_e32 v14, 11, v4
	v_cvt_pk_bf16_f32 v0, v9, v7
	v_cvt_pk_bf16_f32 v1, v11, v39
	v_cvt_pk_bf16_f32 v2, v67, v69
	v_cvt_pk_bf16_f32 v3, v71, v75
	v_lshl_add_u64 v[4:5], v[72:73], 0, v[14:15]
	global_store_dwordx4 v[4:5], v[0:3], off nt
	s_waitcnt lgkmcnt(0)

.LBB0_92:
	s_andn2_b64 vcc, exec, s[0:1]
	s_cbranch_vccnz .LBB0_94
	s_add_i32 s0, s40, 0x4d00
	s_and_b32 s1, s0, 0x1ffc0
	s_and_b32 s0, s38, 0x3e0
	v_or_b32_e32 v0, s0, v41
	v_readlane_b32 s8, v250, 13
	v_lshlrev_b32_e32 v14, 2, v0
	v_readlane_b32 s10, v250, 15
	v_readlane_b32 s11, v250, 16
	v_or_b32_e32 v0, s1, v12
	v_or_b32_e32 v2, s1, v43
	v_lshl_add_u64 v[38:39], s[10:11], 0, v[14:15]
	v_lshlrev_b32_e32 v14, 12, v0
	v_lshl_add_u64 v[0:1], v[38:39], 0, v[14:15]
	v_lshlrev_b32_e32 v14, 12, v2
	v_or_b32_e32 v8, s1, v45
	v_lshl_add_u64 v[4:5], v[38:39], 0, v[14:15]
	v_lshlrev_b32_e32 v14, 12, v8
	v_or_b32_e32 v10, s1, v47
	v_lshl_add_u64 v[8:9], v[38:39], 0, v[14:15]
	v_lshlrev_b32_e32 v14, 12, v10
	v_lshl_add_u64 v[66:67], v[38:39], 0, v[14:15]
	v_or_b32_e32 v14, s1, v48
	v_lshlrev_b32_e32 v14, 12, v14
	v_lshl_add_u64 v[70:71], v[38:39], 0, v[14:15]
	v_or_b32_e32 v14, s1, v49
	v_lshlrev_b32_e32 v14, 12, v14
	v_lshl_add_u64 v[74:75], v[38:39], 0, v[14:15]
	global_load_dwordx4 v[0:3], v[0:1], off
	s_nop 0
	global_load_dwordx4 v[4:7], v[4:5], off
	s_nop 0
	global_load_dwordx4 v[8:11], v[8:9], off
	s_nop 0
	global_load_dwordx4 v[66:69], v[66:67], off
	s_nop 0
	global_load_dwordx4 v[70:73], v[70:71], off
	s_nop 0
	global_load_dwordx4 v[74:77], v[74:75], off
	v_or_b32_e32 v14, s1, v50
	v_lshlrev_b32_e32 v14, 12, v14
	v_lshl_add_u64 v[78:79], v[38:39], 0, v[14:15]
	v_or_b32_e32 v14, s1, v51
	global_load_dwordx4 v[78:81], v[78:79], off
	v_lshlrev_b32_e32 v14, 12, v14
	v_lshl_add_u64 v[38:39], v[38:39], 0, v[14:15]
	global_load_dwordx4 v[82:85], v[38:39], off
	v_add_u32_e32 v65, 0x18c0, v53
	v_add_u32_e32 v92, 0x18c8, v53
	v_add_u32_e32 v93, 0x1ce0, v53
	v_add_u32_e32 v94, 0x1ce8, v53
	v_or_b32_e32 v14, s0, v12
	s_lshl_b32 s28, s1, 1
	v_or_b32_e32 v88, s0, v43
	v_lshl_add_u64 v[38:39], v[34:35], 0, s[28:29]
	v_lshlrev_b32_e32 v14, 11, v14
	v_or_b32_e32 v90, s0, v45
	v_lshl_add_u64 v[86:87], v[38:39], 0, v[14:15]
	v_lshlrev_b32_e32 v14, 11, v88
	v_lshl_add_u64 v[88:89], v[38:39], 0, v[14:15]
	v_lshlrev_b32_e32 v14, 11, v90
	v_lshl_add_u64 v[90:91], v[38:39], 0, v[14:15]
	v_readlane_b32 s9, v250, 14
	v_readlane_b32 s12, v250, 17
	v_readlane_b32 s13, v250, 18
	v_readlane_b32 s14, v250, 19
	v_readlane_b32 s15, v250, 20
	v_readlane_b32 s16, v250, 21
	v_readlane_b32 s17, v250, 22
	v_readlane_b32 s18, v250, 23
	v_readlane_b32 s19, v250, 24
	v_readlane_b32 s20, v250, 25
	v_readlane_b32 s21, v250, 26
	v_readlane_b32 s22, v250, 27
	v_readlane_b32 s23, v250, 28
	s_waitcnt vmcnt(7)
	ds_write2_b32 v53, v0, v1 offset1:1
	ds_write2_b32 v53, v2, v3 offset0:2 offset1:3
	s_waitcnt vmcnt(6)
	ds_write2_b32 v54, v4, v5 offset1:1
	ds_write2_b32 v55, v6, v7 offset1:1
	s_waitcnt vmcnt(5)
	ds_write2_b32 v56, v8, v9 offset1:1
	ds_write2_b32 v57, v10, v11 offset1:1
	s_waitcnt vmcnt(4)
	ds_write2_b32 v58, v66, v67 offset1:1
	ds_write2_b32 v59, v68, v69 offset1:1
	s_waitcnt vmcnt(3)
	ds_write2_b32 v60, v70, v71 offset1:1
	ds_write2_b32 v61, v72, v73 offset1:1
	s_waitcnt vmcnt(2)
	ds_write2_b32 v62, v74, v75 offset1:1
	ds_write2_b32 v63, v76, v77 offset1:1
	s_waitcnt vmcnt(1)
	ds_write2_b32 v65, v78, v79 offset1:1
	ds_write2_b32 v92, v80, v81 offset1:1
	s_waitcnt vmcnt(0)
	ds_write2_b32 v93, v82, v83 offset1:1
	ds_write2_b32 v94, v84, v85 offset1:1
	s_waitcnt lgkmcnt(0)
	ds_read2_b32 v[4:5], v52 offset0:33 offset1:41
	ds_read2_b32 v[6:7], v52 offset1:8
	ds_read2_b32 v[8:9], v52 offset0:66 offset1:74
	ds_read2_b32 v[10:11], v52 offset0:99 offset1:107
	ds_read2_b32 v[66:67], v52 offset0:132 offset1:140
	ds_read2_b32 v[68:69], v52 offset0:165 offset1:173
	ds_read2_b32 v[70:71], v52 offset0:198 offset1:206
	ds_read2_b32 v[72:73], v52 offset0:231 offset1:239
	ds_read2_b32 v[74:75], v52 offset0:49 offset1:57
	ds_read2_b32 v[76:77], v52 offset0:16 offset1:24
	ds_read2_b32 v[78:79], v52 offset0:82 offset1:90
	ds_read2_b32 v[80:81], v52 offset0:115 offset1:123
	ds_read2_b32 v[82:83], v52 offset0:148 offset1:156
	ds_read2_b32 v[84:85], v52 offset0:181 offset1:189
	ds_read2_b32 v[92:93], v52 offset0:214 offset1:222
	ds_read2_b32 v[94:95], v52 offset0:247 offset1:255
	s_waitcnt lgkmcnt(14)
	v_cvt_pk_bf16_f32 v0, v6, v4
	s_waitcnt lgkmcnt(12)
	v_cvt_pk_bf16_f32 v1, v8, v10
	s_waitcnt lgkmcnt(10)
	v_cvt_pk_bf16_f32 v2, v66, v68
	s_waitcnt lgkmcnt(8)
	v_cvt_pk_bf16_f32 v3, v70, v72
	v_cvt_pk_bf16_f32 v4, v7, v5
	v_cvt_pk_bf16_f32 v5, v9, v11
	v_cvt_pk_bf16_f32 v6, v67, v69
	v_cvt_pk_bf16_f32 v7, v71, v73
	s_waitcnt lgkmcnt(6)
	v_cvt_pk_bf16_f32 v8, v76, v74
	s_waitcnt lgkmcnt(4)
	v_cvt_pk_bf16_f32 v9, v78, v80
	s_waitcnt lgkmcnt(2)
	v_cvt_pk_bf16_f32 v10, v82, v84
	s_waitcnt lgkmcnt(0)
	v_cvt_pk_bf16_f32 v11, v92, v94
	global_store_dwordx4 v[86:87], v[0:3], off nt
	global_store_dwordx4 v[88:89], v[4:7], off nt
	global_store_dwordx4 v[90:91], v[8:11], off nt
	v_cvt_pk_bf16_f32 v0, v77, v75
	v_or_b32_e32 v4, s0, v47
	v_lshlrev_b32_e32 v14, 11, v4
	v_cvt_pk_bf16_f32 v1, v79, v81
	v_cvt_pk_bf16_f32 v2, v83, v85
	v_cvt_pk_bf16_f32 v3, v93, v95
	v_lshl_add_u64 v[4:5], v[38:39], 0, v[14:15]
	global_store_dwordx4 v[4:5], v[0:3], off nt
	s_waitcnt lgkmcnt(0)
